# GEMM accumulators zeroed with 64 v_mov_b64 per unit instead of 128 v_mov_b32
# speedup vs baseline: 1.0015x; 1.0015x over previous
; template <class Epi, class Sched, bool ALIGN_EPI = false, bool SP2 = false>
; __device__ __forceinline__ void gemm_phase(PG8_LAS unsigned char* lds, const Gemm g, const Sched& S, const Epi& E) {
;     ...
; #pragma unroll
;         for (int a = 0; a < 2; ++a)
; #pragma unroll
;             for (int b = 0; b < 2; ++b)
; #pragma unroll
;                 for (int m = 0; m < 4; ++m)
; #pragma unroll
;                     for (int n = 0; n < 2; ++n) acc[a][b][m][n] = (f32x4){0.f, 0.f, 0.f, 0.f};
;         cur = nxt; cA = nA; cB = nB; ++ui;
.LBB0_606:
	s_ashr_i32 s23, s22, 31
	s_lshl_b64 s[24:25], s[22:23], 19
	s_add_u32 s24, s8, s24
	s_addc_u32 s25, s9, s25
	s_and_b64 s[26:27], s[2:3], exec
	s_cselect_b32 s23, s25, s29
	s_cselect_b32 s33, s24, s28
	s_ashr_i32 s21, s20, 31
	s_lshl_b64 s[26:27], s[20:21], 19
	s_add_u32 s26, s42, s26
	s_addc_u32 s27, s43, s27
	s_and_b64 s[34:35], s[2:3], exec
	s_cselect_b32 s21, s27, s31
	s_cselect_b32 s56, s26, s30
	s_add_u32 s28, s28, 0x40080
	s_addc_u32 s29, s29, 0
	s_add_u32 s57, s30, 0x100
	s_addc_u32 s58, s31, 0
	s_mov_b32 s59, -2
	v_mov_b64_e32 v[4:5], 0
	v_mov_b64_e32 v[6:7], 0
	v_mov_b64_e32 v[8:9], 0
	v_mov_b64_e32 v[10:11], 0
	v_mov_b64_e32 v[12:13], 0
	v_mov_b64_e32 v[14:15], 0
	v_mov_b64_e32 v[16:17], 0
	v_mov_b64_e32 v[18:19], 0
	v_mov_b64_e32 v[20:21], 0
	v_mov_b64_e32 v[22:23], 0
	v_mov_b64_e32 v[24:25], 0
	v_mov_b64_e32 v[26:27], 0
	v_mov_b64_e32 v[28:29], 0
	v_mov_b64_e32 v[30:31], 0
	v_mov_b64_e32 v[32:33], 0
	v_mov_b64_e32 v[34:35], 0
	v_mov_b64_e32 v[36:37], 0
	v_mov_b64_e32 v[38:39], 0
	v_mov_b64_e32 v[40:41], 0
	v_mov_b64_e32 v[42:43], 0
	v_mov_b64_e32 v[44:45], 0
	v_mov_b64_e32 v[46:47], 0
	v_mov_b64_e32 v[48:49], 0
	v_mov_b64_e32 v[50:51], 0
	v_mov_b64_e32 v[52:53], 0
	v_mov_b64_e32 v[54:55], 0
	v_mov_b64_e32 v[56:57], 0
	v_mov_b64_e32 v[58:59], 0
	v_mov_b64_e32 v[60:61], 0
	v_mov_b64_e32 v[62:63], 0
	v_mov_b64_e32 v[64:65], 0
	v_mov_b64_e32 v[66:67], 0
	v_mov_b64_e32 v[68:69], 0
	v_mov_b64_e32 v[70:71], 0
	v_mov_b64_e32 v[72:73], 0
	v_mov_b64_e32 v[74:75], 0
	v_mov_b64_e32 v[76:77], 0
	v_mov_b64_e32 v[78:79], 0
	v_mov_b64_e32 v[80:81], 0
	v_mov_b64_e32 v[82:83], 0
	v_mov_b64_e32 v[84:85], 0
	v_mov_b64_e32 v[86:87], 0
	v_mov_b64_e32 v[88:89], 0
	v_mov_b64_e32 v[90:91], 0
	v_mov_b64_e32 v[92:93], 0
	v_mov_b64_e32 v[94:95], 0
	v_mov_b64_e32 v[96:97], 0
	v_mov_b64_e32 v[98:99], 0
	v_mov_b64_e32 v[100:101], 0
	v_mov_b64_e32 v[102:103], 0
	v_mov_b64_e32 v[104:105], 0
	v_mov_b64_e32 v[106:107], 0
	v_mov_b64_e32 v[108:109], 0
	v_mov_b64_e32 v[110:111], 0
	v_mov_b64_e32 v[112:113], 0
	v_mov_b64_e32 v[114:115], 0
	v_mov_b64_e32 v[116:117], 0
	v_mov_b64_e32 v[118:119], 0
	v_mov_b64_e32 v[120:121], 0
	v_mov_b64_e32 v[122:123], 0
	v_mov_b64_e32 v[124:125], 0
	v_mov_b64_e32 v[126:127], 0
	v_mov_b64_e32 v[128:129], 0
	v_mov_b64_e32 v[130:131], 0

; template <class Epi, class Sched, bool ALIGN_EPI = false, bool SP2 = false>
; __device__ __forceinline__ void gemm_phase(PG8_LAS unsigned char* lds, const Gemm g, const Sched& S, const Epi& E) {
;     ...
; #pragma unroll
;         for (int a = 0; a < 2; ++a)
; #pragma unroll
;             for (int b = 0; b < 2; ++b)
; #pragma unroll
;                 for (int m = 0; m < 4; ++m)
; #pragma unroll
;                     for (int n = 0; n < 2; ++n) acc[a][b][m][n] = (f32x4){0.f, 0.f, 0.f, 0.f};
;         cur = nxt; cA = nA; cB = nB; ++ui;
.LBB0_637:
	s_add_u32 s26, s26, 0x80
	s_addc_u32 s27, s27, 0
	s_add_u32 s33, s28, 0x100
	s_addc_u32 s54, s29, 0
	s_mov_b32 s28, 0
	s_waitcnt lgkmcnt(0)
	v_mov_b64_e32 v[4:5], 0
	v_mov_b64_e32 v[6:7], 0
	v_mov_b64_e32 v[8:9], 0
	v_mov_b64_e32 v[10:11], 0
	v_mov_b64_e32 v[12:13], 0
	v_mov_b64_e32 v[14:15], 0
	v_mov_b64_e32 v[16:17], 0
	v_mov_b64_e32 v[18:19], 0
	v_mov_b64_e32 v[20:21], 0
	v_mov_b64_e32 v[22:23], 0
	v_mov_b64_e32 v[24:25], 0
	v_mov_b64_e32 v[26:27], 0
	v_mov_b64_e32 v[28:29], 0
	v_mov_b64_e32 v[30:31], 0
	v_mov_b64_e32 v[32:33], 0
	v_mov_b64_e32 v[34:35], 0
	v_mov_b64_e32 v[36:37], 0
	v_mov_b64_e32 v[38:39], 0
	v_mov_b64_e32 v[40:41], 0
	v_mov_b64_e32 v[42:43], 0
	v_mov_b64_e32 v[44:45], 0
	v_mov_b64_e32 v[46:47], 0
	v_mov_b64_e32 v[48:49], 0
	v_mov_b64_e32 v[50:51], 0
	v_mov_b64_e32 v[52:53], 0
	v_mov_b64_e32 v[54:55], 0
	v_mov_b64_e32 v[56:57], 0
	v_mov_b64_e32 v[58:59], 0
	v_mov_b64_e32 v[60:61], 0
	v_mov_b64_e32 v[62:63], 0
	v_mov_b64_e32 v[64:65], 0
	v_mov_b64_e32 v[66:67], 0
	v_mov_b64_e32 v[68:69], 0
	v_mov_b64_e32 v[70:71], 0
	v_mov_b64_e32 v[72:73], 0
	v_mov_b64_e32 v[74:75], 0
	v_mov_b64_e32 v[76:77], 0
	v_mov_b64_e32 v[78:79], 0
	v_mov_b64_e32 v[80:81], 0
	v_mov_b64_e32 v[82:83], 0
	v_mov_b64_e32 v[84:85], 0
	v_mov_b64_e32 v[86:87], 0
	v_mov_b64_e32 v[88:89], 0
	v_mov_b64_e32 v[90:91], 0
	v_mov_b64_e32 v[92:93], 0
	v_mov_b64_e32 v[94:95], 0
	v_mov_b64_e32 v[96:97], 0
	v_mov_b64_e32 v[98:99], 0
	v_mov_b64_e32 v[100:101], 0
	v_mov_b64_e32 v[102:103], 0
	v_mov_b64_e32 v[104:105], 0
	v_mov_b64_e32 v[106:107], 0
	v_mov_b64_e32 v[108:109], 0
	v_mov_b64_e32 v[110:111], 0
	v_mov_b64_e32 v[112:113], 0
	v_mov_b64_e32 v[114:115], 0
	v_mov_b64_e32 v[116:117], 0
	v_mov_b64_e32 v[118:119], 0
	v_mov_b64_e32 v[120:121], 0
	v_mov_b64_e32 v[122:123], 0
	v_mov_b64_e32 v[124:125], 0
	v_mov_b64_e32 v[126:127], 0
	v_mov_b64_e32 v[128:129], 0
	v_mov_b64_e32 v[130:131], 0

; template <class Epi, class Sched, bool ALIGN_EPI = false, bool SP2 = false>
; __device__ __forceinline__ void gemm_phase(PG8_LAS unsigned char* lds, const Gemm g, const Sched& S, const Epi& E) {
;     ...
; #pragma unroll
;         for (int a = 0; a < 2; ++a)
; #pragma unroll
;             for (int b = 0; b < 2; ++b)
; #pragma unroll
;                 for (int m = 0; m < 4; ++m)
; #pragma unroll
;                     for (int n = 0; n < 2; ++n) acc[a][b][m][n] = (f32x4){0.f, 0.f, 0.f, 0.f};
;         cur = nxt; cA = nA; cB = nB; ++ui;
.LBB0_684:
	s_ashr_i32 s35, s34, 31
	s_lshl_b64 s[36:37], s[34:35], 19
	s_add_u32 s36, s24, s36
	s_addc_u32 s37, s25, s37
	s_and_b64 s[38:39], s[2:3], exec
	s_cselect_b32 s33, s37, s43
	s_cselect_b32 s35, s36, s42
	s_ashr_i32 s31, s30, 31
	s_lshl_b64 s[38:39], s[30:31], 19
	s_add_u32 s38, s20, s38
	s_addc_u32 s39, s21, s39
	s_and_b64 s[46:47], s[2:3], exec
	s_cselect_b32 s31, s39, s45
	s_cselect_b32 s65, s38, s44
	s_add_u32 s42, s42, 0x40080
	s_addc_u32 s43, s43, 0
	s_add_u32 s66, s44, 0x100
	s_addc_u32 s67, s45, 0
	s_mov_b32 s68, -2
	v_mov_b64_e32 v[4:5], 0
	v_mov_b64_e32 v[6:7], 0
	v_mov_b64_e32 v[8:9], 0
	v_mov_b64_e32 v[10:11], 0
	v_mov_b64_e32 v[12:13], 0
	v_mov_b64_e32 v[14:15], 0
	v_mov_b64_e32 v[16:17], 0
	v_mov_b64_e32 v[18:19], 0
	v_mov_b64_e32 v[20:21], 0
	v_mov_b64_e32 v[22:23], 0
	v_mov_b64_e32 v[24:25], 0
	v_mov_b64_e32 v[26:27], 0
	v_mov_b64_e32 v[28:29], 0
	v_mov_b64_e32 v[30:31], 0
	v_mov_b64_e32 v[32:33], 0
	v_mov_b64_e32 v[34:35], 0
	v_mov_b64_e32 v[36:37], 0
	v_mov_b64_e32 v[38:39], 0
	v_mov_b64_e32 v[40:41], 0
	v_mov_b64_e32 v[42:43], 0
	v_mov_b64_e32 v[44:45], 0
	v_mov_b64_e32 v[46:47], 0
	v_mov_b64_e32 v[48:49], 0
	v_mov_b64_e32 v[50:51], 0
	v_mov_b64_e32 v[52:53], 0
	v_mov_b64_e32 v[54:55], 0
	v_mov_b64_e32 v[56:57], 0
	v_mov_b64_e32 v[58:59], 0
	v_mov_b64_e32 v[60:61], 0
	v_mov_b64_e32 v[62:63], 0
	v_mov_b64_e32 v[64:65], 0
	v_mov_b64_e32 v[66:67], 0
	v_mov_b64_e32 v[68:69], 0
	v_mov_b64_e32 v[70:71], 0
	v_mov_b64_e32 v[72:73], 0
	v_mov_b64_e32 v[74:75], 0
	v_mov_b64_e32 v[76:77], 0
	v_mov_b64_e32 v[78:79], 0
	v_mov_b64_e32 v[80:81], 0
	v_mov_b64_e32 v[82:83], 0
	v_mov_b64_e32 v[84:85], 0
	v_mov_b64_e32 v[86:87], 0
	v_mov_b64_e32 v[88:89], 0
	v_mov_b64_e32 v[90:91], 0
	v_mov_b64_e32 v[92:93], 0
	v_mov_b64_e32 v[94:95], 0
	v_mov_b64_e32 v[96:97], 0
	v_mov_b64_e32 v[98:99], 0
	v_mov_b64_e32 v[100:101], 0
	v_mov_b64_e32 v[102:103], 0
	v_mov_b64_e32 v[104:105], 0
	v_mov_b64_e32 v[106:107], 0
	v_mov_b64_e32 v[108:109], 0
	v_mov_b64_e32 v[110:111], 0
	v_mov_b64_e32 v[112:113], 0
	v_mov_b64_e32 v[114:115], 0
	v_mov_b64_e32 v[116:117], 0
	v_mov_b64_e32 v[118:119], 0
	v_mov_b64_e32 v[120:121], 0
	v_mov_b64_e32 v[122:123], 0
	v_mov_b64_e32 v[124:125], 0
	v_mov_b64_e32 v[126:127], 0
	v_mov_b64_e32 v[128:129], 0
	v_mov_b64_e32 v[130:131], 0
